# v72 + tiled (LDS-image) layout also for the FFN-down weights: prologue transpose stores FOUT as [N-tile][K-tile][half][16 KiB image] (perm32-inverse row slots); FFN-down stages both operands with cont
# speedup vs baseline: 1.0034x; 1.0034x over previous
; #define PG8_WAIT_V(n) asm volatile("s_waitcnt vmcnt(" #n ")" ::: "memory")
; #define PG8_BAR __builtin_amdgcn_s_barrier()
; template <class Epi, class Sched, bool ALIGN_EPI = false, bool SP2 = false>
; __device__ __forceinline__ void gemm_phase(PG8_LAS unsigned char* lds, const Gemm g, const Sched& S, const Epi& E) {
;     ...
;     for (int i = 0; i < 2; ++i) { int R, C; stage_rc(tid * 16 + i * 8192, R, C); const int Rb = Epi::PERM ? ((R & ~31) + perm32(R & 31)) : R;
;         const int Ra = Epi::APERM ? ((R & ~63) + ((R & 15) << 2) + ((R >> 4) & 3)) : R;
;         voffA[i] = (unsigned)(Ra * K + C) * 2u; voffB[i] = (unsigned)(Rb * K + C) * 2u; }
;     const size_t kstep = (size_t)(BK * 2);
;     const size_t hstep = (size_t)HALF * K * 2;
;     const size_t tstep = 2 * hstep;
;     const unsigned ldsw = (unsigned)wid * 1024u;
;     const int aoff = lds_byte(wr * 64 + fr, fq * 8), boff = lds_byte(wc * 32 + fr, fq * 8);
;     ...
;     Unit cur, nxt; int ui = 0;
;     if (!S.next(0, cur)) return;
;     f32x4 acc[2][2][4][2];
; #pragma unroll
;     for (int a = 0; a < 2; ++a)
; #pragma unroll
;         for (int b = 0; b < 2; ++b)
; #pragma unroll
;             for (int m = 0; m < 4; ++m)
; #pragma unroll
;                 for (int n = 0; n < 2; ++n) acc[a][b][m][n] = (f32x4){0.f, 0.f, 0.f, 0.f};
;     bf16x8 At[4][2], B0[2][2], B1[2][2];
;     const char* cA = (const char*)g.A + (size_t)cur.pm * tstep; const char* cB = (const char*)g.Bt + (size_t)cur.pn * tstep;
;     S.a_ready(cur);
;     if constexpr (SP2) {
;         PG8_STAGE(PG8_SB(0, 0), cB, voffB); PG8_STAGE(PG8_SB(0, 1), cB + hstep, voffB); PG8_STAGE(PG8_SA(0, 0), cA, voffA); PG8_STAGE(PG8_SA(0, 1), cA + hstep, voffA);
;         if (wr == 1) PG8_BAR;
;         PG8_WAIT_V(2); PG8_BAR;
;         PG8_STAGE(PG8_SB(1, 0), cB + kstep, voffB); PG8_STAGE(PG8_SA(1, 0), cA + kstep, voffA); PG8_STAGE(PG8_SB(1, 1), cB + hstep + kstep, voffB);
;         PG8_WAIT_V(6); PG8_BAR;
;     } else {
;         PG8_STAGE(PG8_SB(0, 0), cB, voffB); PG8_STAGE(PG8_SA(0, 0), cA, voffA); PG8_STAGE(PG8_SB(0, 1), cB + hstep, voffB); PG8_STAGE(PG8_SA(0, 1), cA + hstep, voffA);
;         if (wr == 1) PG8_BAR;
;         PG8_WAIT_V(4); PG8_BAR;
;         PG8_STAGE(PG8_SB(1, 0), cB + kstep, voffB); PG8_STAGE(PG8_SA(1, 0), cA + kstep, voffA); PG8_STAGE(PG8_SB(1, 1), cB + hstep + kstep, voffB);
;         PG8_WAIT_V(6); PG8_BAR;
.Ltl_a:
	v_add_lshl_u32 v0, v3, v0, 1
	s_cmp_lg_u32 s98, 0x8000
	s_cbranch_scc1 .Ltl_d
	v_lshlrev_b32_e32 v0, 4, v246
.Ltl_d:
	v_ashrrev_i32_e32 v3, 31, v2
	v_lshrrev_b32_e32 v3, 22, v3
	v_add_u32_e32 v3, v2, v3
	v_ashrrev_i32_e32 v3, 10, v3
	v_mul_i32_i24_e32 v4, 0x400, v3
	v_sub_u32_e32 v2, v2, v4
	v_lshrrev_b32_e32 v4, 4, v2
	v_bitop3_b32 v2, v4, v2, 32 bitop3:0x6c
	v_ashrrev_i32_e32 v5, 31, v2
	v_lshrrev_b32_e32 v5, 26, v5
	v_lshlrev_b32_e32 v4, 3, v3
	v_add_u32_e32 v5, v2, v5
	v_and_b32_e32 v4, -16, v4
	v_ashrrev_i32_e32 v6, 6, v5
	v_add_u32_e32 v4, v6, v4
	v_and_b32_e32 v6, 3, v6
	v_lshlrev_b32_e32 v3, 5, v3
	v_and_or_b32 v6, v4, s5, v6
	s_ashr_i32 s5, s67, 6
	s_lshl_b32 s29, s11, 9
	s_ashr_i32 s4, s67, 8
	v_and_b32_e32 v17, 32, v3
	v_and_b32_e32 v3, 0xc0, v5
	s_lshl_b32 s58, s11, 8
	s_lshl_b32 s80, s5, 10
	s_mul_i32 s7, s29, s83
	v_sub_u32_e32 v2, v2, v3
	v_lshlrev_b32_e32 v3, 1, v4
	v_lshrrev_b32_e32 v5, 2, v4
	s_mul_hi_i32 s6, s29, s83
	s_add_u32 s8, s20, s7
	v_ashrrev_i16_sdwa v2, v244, sext(v2) dst_sel:DWORD dst_unused:UNUSED_PAD src0_sel:DWORD src1_sel:BYTE_0
	v_and_b32_e32 v3, 24, v3
	v_and_b32_e32 v5, 4, v5
	s_addc_u32 s9, s21, s6
	s_add_i32 s81, s80, 0
	v_bfe_i32 v18, v2, 0, 16
	v_or3_b32 v3, v6, v5, v3
	s_add_i32 m0, s81, 0x10000
	v_add_u32_e32 v2, v17, v18
	v_mul_lo_u32 v3, v3, s11
	global_load_lds_dwordx4 v0, s[8:9]
	s_add_i32 m0, s81, 0x12000
	v_add_lshl_u32 v198, v3, v2, 1
	s_cmp_lg_u32 s98, 0x8000
	s_cbranch_scc1 .Ltl_e
	v_add_u32_e32 v198, 0x2000, v0
.Ltl_e:
	s_add_u32 s6, s8, s100
	global_load_lds_dwordx4 v198, s[8:9]
	s_addc_u32 s7, s9, 0
	s_add_i32 m0, s81, 0x14000
	s_mul_i32 s69, s29, s66
	v_mov_b32_e32 v199, v1
	global_load_lds_dwordx4 v0, s[6:7]
	s_add_i32 m0, s81, 0x16000
	s_mul_hi_i32 s12, s29, s66
	v_lshl_add_u64 v[6:7], s[6:7], 0, v[0:1]
	v_lshl_add_u64 v[8:9], s[6:7], 0, v[198:199]
	global_load_lds_dwordx4 v198, s[6:7]
	s_add_u32 s6, s40, s69
	s_addc_u32 s7, s41, s12
	s_add_i32 s70, s81, 0x2000
	v_mul_lo_u32 v19, v4, s11
	s_mov_b32 m0, s81
	s_add_u32 s84, s6, s100
	v_add_lshl_u32 v196, v2, v19, 1
	global_load_lds_dwordx4 v194, s[6:7]
	s_mov_b32 m0, s70
	s_addc_u32 s85, s7, 0
	s_add_i32 s71, s81, 0x4000
	s_cmp_lg_u32 s98, 0x8000
	s_cbranch_scc1 .Ltl_b
	v_add_u32_e32 v196, 0x2000, v194

; #define PG8_STAGE(bufoff, gbase, voff) do { _Pragma("unroll") for (int _i = 0; _i < 2; ++_i) \
;         __builtin_amdgcn_global_load_lds((const unsigned*)((const char*)(gbase) + (voff)[_i]), (PG8_LAS unsigned*)(lds + (bufoff) + ldsw + _i * 8192), 16, 0, 0); } while (0)
; #define PG8_WAIT_V(n) asm volatile("s_waitcnt vmcnt(" #n ")" ::: "memory")
; #define PG8_BAR __builtin_amdgcn_s_barrier()
; template <class Epi, class Sched, bool ALIGN_EPI = false, bool SP2 = false>
; __device__ __forceinline__ void gemm_phase(PG8_LAS unsigned char* lds, const Gemm g, const Sched& S, const Epi& E) {
;     ...
;         PG8_STAGE(PG8_SB(0, 0), cB, voffB); PG8_STAGE(PG8_SA(0, 0), cA, voffA); PG8_STAGE(PG8_SB(0, 1), cB + hstep, voffB); PG8_STAGE(PG8_SA(0, 1), cA + hstep, voffA);
;         if (wr == 1) PG8_BAR;
;         PG8_WAIT_V(4); PG8_BAR;
;         PG8_STAGE(PG8_SB(1, 0), cB + kstep, voffB); PG8_STAGE(PG8_SA(1, 0), cA + kstep, voffA); PG8_STAGE(PG8_SB(1, 1), cB + hstep + kstep, voffB);
;         PG8_WAIT_V(6); PG8_BAR;
.LBB0_165:
	v_readlane_b32 s16, v254, 36
	v_readlane_b32 s17, v254, 37
	s_cmp_lt_i32 s16, 26
	s_cselect_b64 s[84:85], -1, 0
	v_readlane_b32 s16, v252, 37
	s_or_b64 s[0:1], s[84:85], s[0:1]
	v_readlane_b32 s17, v252, 38
	s_and_b64 s[0:1], s[16:17], s[0:1]
	s_and_b64 s[0:1], s[0:1], exec
	s_cselect_b32 s82, s13, -1
	s_lshl_b32 s0, s4, 6
	v_and_b32_e32 v21, 48, v20
	v_lshlrev_b32_e32 v22, 6, v20
	s_movk_i32 s1, 0x3c0
	v_lshlrev_b32_e32 v20, 2, v20
	v_readlane_b32 s18, v254, 38
	v_readlane_b32 s19, v254, 39
	s_and_b32 s43, s5, 3
	v_writelane_b32 v254, s0, 42
	s_lshl_b32 s0, s4, 13
	v_and_or_b32 v21, v22, s1, v21
	v_and_b32_e32 v20, 32, v20
	v_bitop3_b32 v22, v21, s0, v20 bitop3:0xde
	s_lshl_b32 s0, s43, 12
	v_bitop3_b32 v248, v21, s0, v20 bitop3:0xde
	s_mul_i32 s0, s37, 0xc000
	s_add_i32 s0, s0, s10
	s_ashr_i32 s1, s0, 31
	s_lshr_b32 s69, s11, 6
	s_lshl_b32 s36, s43, 5
	s_lshl_b64 s[0:1], s[0:1], 3
	s_add_u32 s44, s34, s0
	s_addc_u32 s45, s35, s1
	s_add_i32 m0, s81, 0x18000
	v_lshl_add_u64 v[2:3], v[2:3], 0, s[98:99]
	s_waitcnt vmcnt(2)
	s_barrier
	global_load_lds_dwordx4 v[2:3], off
	v_lshl_add_u64 v[2:3], v[4:5], 0, s[98:99]
	s_add_i32 m0, s81, 0x1a000
	s_add_i32 s10, s81, 0x8000
	global_load_lds_dwordx4 v[2:3], off
	v_lshl_add_u64 v[2:3], v[10:11], 0, s[98:99]
	s_mov_b32 m0, s10
	s_add_i32 s11, s81, 0xa000
	global_load_lds_dwordx4 v[2:3], off
	v_lshl_add_u64 v[2:3], v[12:13], 0, s[98:99]
	s_mov_b32 m0, s11
	s_add_i32 s13, s69, -2
	global_load_lds_dwordx4 v[2:3], off
	s_add_i32 m0, s81, 0x1c000
	v_lshl_add_u64 v[2:3], v[6:7], 0, s[98:99]
	global_load_lds_dwordx4 v[2:3], off
	v_lshl_add_u64 v[2:3], v[8:9], 0, s[98:99]
	s_add_i32 m0, s81, 0x1e000
	s_cmpk_lt_u32 s67, 0x100
	global_load_lds_dwordx4 v[2:3], off
	s_cselect_b64 s[46:47], -1, 0
	s_ashr_i32 s39, s23, 31
	s_cmp_gt_i32 s82, -1
	s_cselect_b64 s[48:49], -1, 0
	s_mul_hi_u32 s4, s82, 0x6000
	s_mul_i32 s5, s82, 0x6000
	s_and_b64 s[0:1], s[48:49], exec
	s_cselect_b32 s1, s4, 0
	s_cselect_b32 s0, s5, 0
	s_lshl_b64 s[0:1], s[0:1], 2
	v_readlane_b32 s16, v252, 52
	v_readlane_b32 s17, v252, 53
	s_add_u32 s50, s16, s0
	s_addc_u32 s51, s17, s1
	v_readlane_b32 s0, v252, 54
	v_add_u32_e32 v2, v16, v14
	s_add_u32 s0, s0, s5
	v_add_lshl_u32 v2, v2, v15, 1
	v_mov_b32_e32 v3, v1
	s_waitcnt vmcnt(6)
	v_writelane_b32 v254, s0, 44
	v_readlane_b32 s0, v252, 55
	v_lshl_add_u64 v[200:201], s[58:59], 0, v[2:3]
	v_add_u32_e32 v2, v19, v17
	s_addc_u32 s0, s0, s4
	v_add_lshl_u32 v2, v2, v18, 1
	s_mov_b32 s82, 0
	v_writelane_b32 v254, s0, 50
	v_lshl_add_u64 v[210:211], s[58:59], 0, v[2:3]
	s_cmp_lg_u32 s98, 0x8000
	s_cbranch_scc1 .Ltl_c
	v_add_u32_e32 v200, 0x4000, v194
	v_mov_b32_e32 v201, 0
	v_add_u32_e32 v210, 0x4000, v196
	v_mov_b32_e32 v211, 0

; #define PG8_STAGE(bufoff, gbase, voff) do { _Pragma("unroll") for (int _i = 0; _i < 2; ++_i) \
;         __builtin_amdgcn_global_load_lds((const unsigned*)((const char*)(gbase) + (voff)[_i]), (PG8_LAS unsigned*)(lds + (bufoff) + ldsw + _i * 8192), 16, 0, 0); } while (0)
; #define PG8_LDA(dst, b, h) do { _Pragma("unroll") for (int m = 0; m < 4; ++m) _Pragma("unroll") for (int k = 0; k < 2; ++k) dst[m][k] = *(const PG8_LAS bf16x8*)(lds + PG8_SA(b, h) + aoff + m * 2048 + k * 1024); } while (0)
; #define PG8_LDB(dst, b, h) do { _Pragma("unroll") for (int n = 0; n < 2; ++n) _Pragma("unroll") for (int k = 0; k < 2; ++k) dst[n][k] = *(const PG8_LAS bf16x8*)(lds + PG8_SB(b, h) + boff + n * 2048 + k * 1024); } while (0)
; #define PG8_WAIT_V(n) asm volatile("s_waitcnt vmcnt(" #n ")" ::: "memory")
; #define PG8_WAIT_L(n) asm volatile("s_waitcnt lgkmcnt(" #n ")" ::: "memory")
; #define PG8_BAR __builtin_amdgcn_s_barrier()
; #define PG8_SCHED __builtin_amdgcn_sched_barrier(0)
; template <class Epi, class Sched, bool ALIGN_EPI = false, bool SP2 = false>
; __device__ __forceinline__ void gemm_phase(PG8_LAS unsigned char* lds, const Gemm g, const Sched& S, const Epi& E) {
;     ...
;         const bool has_next = S.next(ui + 1, nxt);
;         const char* nA = has_next ? (const char*)g.A + (size_t)nxt.pm * tstep : cA; const char* nB = has_next ? (const char*)g.Bt + (size_t)nxt.pn * tstep : cB;
;         for (int t = 0; t < nt; t += 2) {
;             const bool last = (t == nt - 2);
;             const char* a1 = cA + (size_t)(t + 1) * kstep;
;             const char* a2 = last ? nA : cA + (size_t)(t + 2) * kstep; const char* b2 = last ? nB : cB + (size_t)(t + 2) * kstep;
;             const char* a3 = a2 + kstep; const char* b3 = b2 + kstep;
;             if (last && has_next) S.a_ready(nxt);
;             if constexpr (SP2) {
;             PG8_LDB(B0, 0, 0); PG8_LDB(B1, 0, 1); PG8_SCHED; PG8_LDA(At, 0, 0); PG8_STAGE(PG8_SA(1, 1), a1 + hstep, voffA);
;             PG8_WAIT_V(8); PG8_WAIT_L(0); PG8_BAR; PG8_MMA(0, 0, At, B0); PG8_MMA(0, 1, At, B1); PG8_BAR; PG8_SCHED;
;             PG8_LDA(At, 0, 1); PG8_STAGE(PG8_SB(0, 0), b2, voffB); PG8_STAGE(PG8_SB(0, 1), b2 + hstep, voffB); PG8_STAGE(PG8_SA(0, 0), a2, voffA);
;             PG8_WAIT_V(8); PG8_WAIT_L(0); PG8_BAR; PG8_MMA(1, 0, At, B0); PG8_MMA(1, 1, At, B1); PG8_BAR; PG8_SCHED;
.LBB0_174:
	s_add_u32 s6, s6, s98
	s_addc_u32 s7, s7, 0
	s_add_u32 s67, s8, s98
	s_addc_u32 s85, s9, 0
	s_add_u32 s67, s67, s98
	s_addc_u32 s85, s85, 0
	s_mov_b32 s8, 0
	s_waitcnt vmcnt(0)
.Lpeel175:
	s_add_i32 vcc_lo, s8, 2
	s_add_u32 s4, s6, s98
	s_addc_u32 s5, s7, 0
	s_add_i32 vcc_hi, 0, 0x10000
	s_cmp_eq_u32 s13, s8
	s_cselect_b32 s9, s1, s5
	s_cselect_b32 s8, s0, s4
	s_cselect_b32 s5, s97, s85
	s_cselect_b32 s4, s96, s67
	s_add_i32 s84, 0, 0x14000
	v_add_u32_e32 v122, vcc_hi, v248
	v_add_u32_e32 v154, s84, v248
	ds_read_b128 v[98:101], v122
	ds_read_b128 v[102:105], v122 offset:1024
	ds_read_b128 v[114:117], v122 offset:2048
	ds_read_b128 v[122:125], v122 offset:3072
	ds_read_b128 v[130:133], v154
	ds_read_b128 v[138:141], v154 offset:1024
	ds_read_b128 v[146:149], v154 offset:2048
	ds_read_b128 v[154:157], v154 offset:3072
	v_lshl_add_u64 v[206:207], s[6:7], 0, v[200:201]
	s_add_i32 m0, s81, 0xc000
	ds_read_b128 v[162:165], v249
	ds_read_b128 v[166:169], v249 offset:1024
	ds_read_b128 v[170:173], v249 offset:2048
	ds_read_b128 v[174:177], v249 offset:3072
	ds_read_b128 v[178:181], v249 offset:4096
	ds_read_b128 v[182:185], v249 offset:5120
	ds_read_b128 v[186:189], v249 offset:6144
	ds_read_b128 v[190:193], v249 offset:7168
	global_load_lds_dwordx4 v[206:207], off
	v_lshl_add_u64 v[206:207], s[6:7], 0, v[210:211]
	s_add_i32 m0, s81, 0xe000
	s_nop 0
	global_load_lds_dwordx4 v[206:207], off
	s_waitcnt vmcnt(8)
	s_waitcnt lgkmcnt(0)
	s_barrier
	s_setprio 1
	s_waitcnt lgkmcnt(0)
	v_mfma_f32_16x16x32_bf16 v[158:161], v[98:101], v[162:165], 0
	v_mfma_f32_16x16x32_bf16 v[150:153], v[114:117], v[162:165], 0
	v_mfma_f32_16x16x32_bf16 v[118:121], v[114:117], v[170:173], 0
	v_mfma_f32_16x16x32_bf16 v[126:129], v[98:101], v[170:173], 0
	v_mfma_f32_16x16x32_bf16 v[94:97], v[98:101], v[178:181], 0
	v_mfma_f32_16x16x32_bf16 v[90:93], v[114:117], v[178:181], 0
	v_mfma_f32_16x16x32_bf16 v[74:77], v[114:117], v[186:189], 0
	v_mfma_f32_16x16x32_bf16 v[78:81], v[98:101], v[186:189], 0
	v_mfma_f32_16x16x32_bf16 v[158:161], v[102:105], v[166:169], v[158:161]
	v_mfma_f32_16x16x32_bf16 v[150:153], v[122:125], v[166:169], v[150:153]
	v_mfma_f32_16x16x32_bf16 v[118:121], v[122:125], v[174:177], v[118:121]
	v_mfma_f32_16x16x32_bf16 v[126:129], v[102:105], v[174:177], v[126:129]
	v_mfma_f32_16x16x32_bf16 v[94:97], v[102:105], v[182:185], v[94:97]
	v_mfma_f32_16x16x32_bf16 v[90:93], v[122:125], v[182:185], v[90:93]
	v_mfma_f32_16x16x32_bf16 v[74:77], v[122:125], v[190:193], v[74:77]
	v_mfma_f32_16x16x32_bf16 v[78:81], v[102:105], v[190:193], v[78:81]
	s_setprio 0
	s_setprio 1
	v_mfma_f32_16x16x32_bf16 v[142:145], v[130:133], v[162:165], 0
	v_mfma_f32_16x16x32_bf16 v[134:137], v[146:149], v[162:165], 0
	v_mfma_f32_16x16x32_bf16 v[106:109], v[146:149], v[170:173], 0
	v_mfma_f32_16x16x32_bf16 v[110:113], v[130:133], v[170:173], 0
	v_mfma_f32_16x16x32_bf16 v[86:89], v[130:133], v[178:181], 0
	v_mfma_f32_16x16x32_bf16 v[82:85], v[146:149], v[178:181], 0
	v_mfma_f32_16x16x32_bf16 v[66:69], v[146:149], v[186:189], 0
	v_mfma_f32_16x16x32_bf16 v[70:73], v[130:133], v[186:189], 0
	v_mfma_f32_16x16x32_bf16 v[142:145], v[138:141], v[166:169], v[142:145]
	v_mfma_f32_16x16x32_bf16 v[134:137], v[154:157], v[166:169], v[134:137]
	v_mfma_f32_16x16x32_bf16 v[106:109], v[154:157], v[174:177], v[106:109]
	v_mfma_f32_16x16x32_bf16 v[110:113], v[138:141], v[174:177], v[110:113]
	v_mfma_f32_16x16x32_bf16 v[86:89], v[138:141], v[182:185], v[86:89]
	v_mfma_f32_16x16x32_bf16 v[82:85], v[154:157], v[182:185], v[82:85]
	v_mfma_f32_16x16x32_bf16 v[66:69], v[154:157], v[190:193], v[66:69]
	v_mfma_f32_16x16x32_bf16 v[70:73], v[138:141], v[190:193], v[70:73]
	s_setprio 0
	s_barrier
	s_add_i32 vcc_hi, vcc_hi, s80
	v_lshl_add_u64 v[206:207], s[4:5], 0, v[0:1]
	s_mov_b32 m0, vcc_hi
	ds_read_b128 v[162:165], v249 offset:16384
	ds_read_b128 v[166:169], v249 offset:17408
	ds_read_b128 v[170:173], v249 offset:18432
	ds_read_b128 v[174:177], v249 offset:19456
	ds_read_b128 v[178:181], v249 offset:20480
	ds_read_b128 v[182:185], v249 offset:21504
	ds_read_b128 v[186:189], v249 offset:22528
	ds_read_b128 v[190:193], v249 offset:23552
	global_load_lds_dwordx4 v[206:207], off
	s_add_i32 m0, vcc_hi, 0x2000
	v_lshl_add_u64 v[212:213], s[4:5], 0, v[198:199]
	s_add_u32 s4, s4, s100
	s_addc_u32 s5, s5, 0
	s_add_i32 s84, s84, s80
	global_load_lds_dwordx4 v[212:213], off
	v_lshl_add_u64 v[214:215], s[4:5], 0, v[0:1]
	s_mov_b32 m0, s84
	v_lshl_add_u64 v[216:217], s[4:5], 0, v[198:199]
	global_load_lds_dwordx4 v[214:215], off
	s_add_i32 m0, s84, 0x2000
	v_lshl_add_u64 v[218:219], s[8:9], 0, v[194:195]
	global_load_lds_dwordx4 v[216:217], off
	s_mov_b32 m0, s81
	v_lshl_add_u64 v[220:221], s[8:9], 0, v[196:197]
	global_load_lds_dwordx4 v[218:219], off
	s_mov_b32 m0, s70
	s_nop 0
	global_load_lds_dwordx4 v[220:221], off
	s_waitcnt vmcnt(8)
	s_waitcnt lgkmcnt(0)
	s_barrier
; #define PG8_STAGE(bufoff, gbase, voff) do { _Pragma("unroll") for (int _i = 0; _i < 2; ++_i) \
;         __builtin_amdgcn_global_load_lds((const unsigned*)((const char*)(gbase) + (voff)[_i]), (PG8_LAS unsigned*)(lds + (bufoff) + ldsw + _i * 8192), 16, 0, 0); } while (0)
; #define PG8_LDA(dst, b, h) do { _Pragma("unroll") for (int m = 0; m < 4; ++m) _Pragma("unroll") for (int k = 0; k < 2; ++k) dst[m][k] = *(const PG8_LAS bf16x8*)(lds + PG8_SA(b, h) + aoff + m * 2048 + k * 1024); } while (0)
; #define PG8_LDB(dst, b, h) do { _Pragma("unroll") for (int n = 0; n < 2; ++n) _Pragma("unroll") for (int k = 0; k < 2; ++k) dst[n][k] = *(const PG8_LAS bf16x8*)(lds + PG8_SB(b, h) + boff + n * 2048 + k * 1024); } while (0)
; #define PG8_MMA(ai, bj, At, Bt) do { __builtin_amdgcn_s_setprio(1); _Pragma("unroll") for (int m = 0; m < 4; ++m) _Pragma("unroll") for (int n = 0; n < 2; ++n) _Pragma("unroll") for (int k = 0; k < 2; ++k) \
;         acc[ai][bj][m][n] = mma16<Epi::I8>(Bt[n][k], At[m][k], acc[ai][bj][m][n]); __builtin_amdgcn_s_setprio(0); } while (0)
; #define PG8_WAIT_V(n) asm volatile("s_waitcnt vmcnt(" #n ")" ::: "memory")
; #define PG8_WAIT_L(n) asm volatile("s_waitcnt lgkmcnt(" #n ")" ::: "memory")
; #define PG8_BAR __builtin_amdgcn_s_barrier()
; #define PG8_SCHED __builtin_amdgcn_sched_barrier(0)
; template <class Epi, class Sched, bool ALIGN_EPI = false, bool SP2 = false>
; __device__ __forceinline__ void gemm_phase(PG8_LAS unsigned char* lds, const Gemm g, const Sched& S, const Epi& E) {
;     ...
;             PG8_WAIT_V(8); PG8_WAIT_L(0); PG8_BAR; PG8_MMA(0, 0, At, B0); PG8_MMA(0, 1, At, B1); PG8_BAR; PG8_SCHED;
;             PG8_LDA(At, 0, 1); PG8_STAGE(PG8_SB(0, 0), b2, voffB); PG8_STAGE(PG8_SB(0, 1), b2 + hstep, voffB); PG8_STAGE(PG8_SA(0, 0), a2, voffA);
;             PG8_WAIT_V(8); PG8_WAIT_L(0); PG8_BAR; PG8_MMA(1, 0, At, B0); PG8_MMA(1, 1, At, B1); PG8_BAR; PG8_SCHED;
;             PG8_LDB(B0, 1, 0); PG8_LDB(B1, 1, 1); PG8_SCHED; PG8_LDA(At, 1, 0); PG8_STAGE(PG8_SA(0, 1), a2 + hstep, voffA);
;             PG8_WAIT_V(8); PG8_WAIT_L(0); PG8_BAR; PG8_MMA(0, 0, At, B0); PG8_MMA(0, 1, At, B1); PG8_BAR; PG8_SCHED;
	s_setprio 1
	s_waitcnt lgkmcnt(0)
	v_mfma_f32_16x16x32_bf16 v[62:65], v[98:101], v[162:165], 0
	v_mfma_f32_16x16x32_bf16 v[58:61], v[114:117], v[162:165], 0
	v_mfma_f32_16x16x32_bf16 v[42:45], v[114:117], v[170:173], 0
	v_mfma_f32_16x16x32_bf16 v[46:49], v[98:101], v[170:173], 0
	v_mfma_f32_16x16x32_bf16 v[30:33], v[98:101], v[178:181], 0
	v_mfma_f32_16x16x32_bf16 v[26:29], v[114:117], v[178:181], 0
	v_mfma_f32_16x16x32_bf16 v[10:13], v[114:117], v[186:189], 0
	v_mfma_f32_16x16x32_bf16 v[14:17], v[98:101], v[186:189], 0
	v_mfma_f32_16x16x32_bf16 v[62:65], v[102:105], v[166:169], v[62:65]
	v_mfma_f32_16x16x32_bf16 v[58:61], v[122:125], v[166:169], v[58:61]
	v_mfma_f32_16x16x32_bf16 v[42:45], v[122:125], v[174:177], v[42:45]
	v_mfma_f32_16x16x32_bf16 v[46:49], v[102:105], v[174:177], v[46:49]
	v_mfma_f32_16x16x32_bf16 v[30:33], v[102:105], v[182:185], v[30:33]
	v_mfma_f32_16x16x32_bf16 v[26:29], v[122:125], v[182:185], v[26:29]
	v_mfma_f32_16x16x32_bf16 v[10:13], v[122:125], v[190:193], v[10:13]
	v_mfma_f32_16x16x32_bf16 v[14:17], v[102:105], v[190:193], v[14:17]
	s_setprio 0
	s_setprio 1
	v_mfma_f32_16x16x32_bf16 v[54:57], v[130:133], v[162:165], 0
	v_mfma_f32_16x16x32_bf16 v[50:53], v[146:149], v[162:165], 0
	v_mfma_f32_16x16x32_bf16 v[34:37], v[146:149], v[170:173], 0
	v_mfma_f32_16x16x32_bf16 v[38:41], v[130:133], v[170:173], 0
	v_mfma_f32_16x16x32_bf16 v[22:25], v[130:133], v[178:181], 0
	v_mfma_f32_16x16x32_bf16 v[18:21], v[146:149], v[178:181], 0
	v_mfma_f32_16x16x32_bf16 v[2:5], v[146:149], v[186:189], 0
	v_mfma_f32_16x16x32_bf16 v[6:9], v[130:133], v[186:189], 0
	v_mfma_f32_16x16x32_bf16 v[54:57], v[138:141], v[166:169], v[54:57]
	v_mfma_f32_16x16x32_bf16 v[50:53], v[154:157], v[166:169], v[50:53]
	v_mfma_f32_16x16x32_bf16 v[34:37], v[154:157], v[174:177], v[34:37]
	v_mfma_f32_16x16x32_bf16 v[38:41], v[138:141], v[174:177], v[38:41]
	v_mfma_f32_16x16x32_bf16 v[22:25], v[138:141], v[182:185], v[22:25]
	v_mfma_f32_16x16x32_bf16 v[18:21], v[154:157], v[182:185], v[18:21]
	v_mfma_f32_16x16x32_bf16 v[2:5], v[154:157], v[190:193], v[2:5]
	v_mfma_f32_16x16x32_bf16 v[6:9], v[138:141], v[190:193], v[6:9]
	s_setprio 0
	s_barrier
	s_add_i32 s84, 0, 0x18000
	s_add_i32 vcc_hi, 0, 0x1c000
	v_add_u32_e32 v122, s84, v248
	v_add_u32_e32 v154, vcc_hi, v248
	ds_read_b128 v[98:101], v122
	ds_read_b128 v[102:105], v122 offset:1024
	ds_read_b128 v[114:117], v122 offset:2048
	ds_read_b128 v[122:125], v122 offset:3072
	ds_read_b128 v[130:133], v154
	ds_read_b128 v[138:141], v154 offset:1024
	ds_read_b128 v[146:149], v154 offset:2048
	ds_read_b128 v[154:157], v154 offset:3072
	s_add_u32 s4, s8, s100
	s_addc_u32 s5, s9, 0
	s_mov_b32 m0, s71
	v_lshl_add_u64 v[222:223], s[4:5], 0, v[194:195]
	ds_read_b128 v[162:165], v249 offset:32768
	ds_read_b128 v[166:169], v249 offset:33792
	ds_read_b128 v[170:173], v249 offset:34816
	ds_read_b128 v[174:177], v249 offset:35840
	ds_read_b128 v[178:181], v249 offset:36864
	ds_read_b128 v[182:185], v249 offset:37888
	ds_read_b128 v[186:189], v249 offset:38912
	ds_read_b128 v[190:193], v249 offset:39936
	global_load_lds_dwordx4 v[222:223], off
	v_lshl_add_u64 v[222:223], s[4:5], 0, v[196:197]
	s_mov_b32 m0, s12
	s_nop 0
	global_load_lds_dwordx4 v[222:223], off
	s_waitcnt vmcnt(8)
	s_waitcnt lgkmcnt(0)
	s_barrier
	s_setprio 1
	s_waitcnt lgkmcnt(0)
	v_mfma_f32_16x16x32_bf16 v[158:161], v[98:101], v[162:165], v[158:161]
	v_mfma_f32_16x16x32_bf16 v[150:153], v[114:117], v[162:165], v[150:153]
	v_mfma_f32_16x16x32_bf16 v[118:121], v[114:117], v[170:173], v[118:121]
	v_mfma_f32_16x16x32_bf16 v[126:129], v[98:101], v[170:173], v[126:129]
	v_mfma_f32_16x16x32_bf16 v[94:97], v[98:101], v[178:181], v[94:97]
	v_mfma_f32_16x16x32_bf16 v[90:93], v[114:117], v[178:181], v[90:93]
	v_mfma_f32_16x16x32_bf16 v[74:77], v[114:117], v[186:189], v[74:77]
	v_mfma_f32_16x16x32_bf16 v[78:81], v[98:101], v[186:189], v[78:81]
	v_mfma_f32_16x16x32_bf16 v[158:161], v[102:105], v[166:169], v[158:161]
	v_mfma_f32_16x16x32_bf16 v[150:153], v[122:125], v[166:169], v[150:153]
	v_mfma_f32_16x16x32_bf16 v[118:121], v[122:125], v[174:177], v[118:121]
	v_mfma_f32_16x16x32_bf16 v[126:129], v[102:105], v[174:177], v[126:129]
	v_mfma_f32_16x16x32_bf16 v[94:97], v[102:105], v[182:185], v[94:97]
	v_mfma_f32_16x16x32_bf16 v[90:93], v[122:125], v[182:185], v[90:93]
	v_mfma_f32_16x16x32_bf16 v[74:77], v[122:125], v[190:193], v[74:77]
	v_mfma_f32_16x16x32_bf16 v[78:81], v[102:105], v[190:193], v[78:81]
	s_setprio 0
	s_setprio 1
	v_mfma_f32_16x16x32_bf16 v[142:145], v[130:133], v[162:165], v[142:145]
	v_mfma_f32_16x16x32_bf16 v[134:137], v[146:149], v[162:165], v[134:137]
	v_mfma_f32_16x16x32_bf16 v[106:109], v[146:149], v[170:173], v[106:109]
	v_mfma_f32_16x16x32_bf16 v[110:113], v[130:133], v[170:173], v[110:113]
	v_mfma_f32_16x16x32_bf16 v[86:89], v[130:133], v[178:181], v[86:89]
	v_mfma_f32_16x16x32_bf16 v[82:85], v[146:149], v[178:181], v[82:85]
	v_mfma_f32_16x16x32_bf16 v[66:69], v[146:149], v[186:189], v[66:69]
	v_mfma_f32_16x16x32_bf16 v[70:73], v[130:133], v[186:189], v[70:73]
	v_mfma_f32_16x16x32_bf16 v[142:145], v[138:141], v[166:169], v[142:145]
	v_mfma_f32_16x16x32_bf16 v[134:137], v[154:157], v[166:169], v[134:137]
	v_mfma_f32_16x16x32_bf16 v[106:109], v[154:157], v[174:177], v[106:109]
	v_mfma_f32_16x16x32_bf16 v[110:113], v[138:141], v[174:177], v[110:113]
	v_mfma_f32_16x16x32_bf16 v[86:89], v[138:141], v[182:185], v[86:89]
	v_mfma_f32_16x16x32_bf16 v[82:85], v[154:157], v[182:185], v[82:85]
	v_mfma_f32_16x16x32_bf16 v[66:69], v[154:157], v[190:193], v[66:69]
	v_mfma_f32_16x16x32_bf16 v[70:73], v[138:141], v[190:193], v[70:73]
	s_setprio 0
	s_barrier
; #define PG8_STAGE(bufoff, gbase, voff) do { _Pragma("unroll") for (int _i = 0; _i < 2; ++_i) \
;         __builtin_amdgcn_global_load_lds((const unsigned*)((const char*)(gbase) + (voff)[_i]), (PG8_LAS unsigned*)(lds + (bufoff) + ldsw + _i * 8192), 16, 0, 0); } while (0)
; #define PG8_LDA(dst, b, h) do { _Pragma("unroll") for (int m = 0; m < 4; ++m) _Pragma("unroll") for (int k = 0; k < 2; ++k) dst[m][k] = *(const PG8_LAS bf16x8*)(lds + PG8_SA(b, h) + aoff + m * 2048 + k * 1024); } while (0)
; #define PG8_LDB(dst, b, h) do { _Pragma("unroll") for (int n = 0; n < 2; ++n) _Pragma("unroll") for (int k = 0; k < 2; ++k) dst[n][k] = *(const PG8_LAS bf16x8*)(lds + PG8_SB(b, h) + boff + n * 2048 + k * 1024); } while (0)
; #define PG8_MMA(ai, bj, At, Bt) do { __builtin_amdgcn_s_setprio(1); _Pragma("unroll") for (int m = 0; m < 4; ++m) _Pragma("unroll") for (int n = 0; n < 2; ++n) _Pragma("unroll") for (int k = 0; k < 2; ++k) \
;         acc[ai][bj][m][n] = mma16<Epi::I8>(Bt[n][k], At[m][k], acc[ai][bj][m][n]); __builtin_amdgcn_s_setprio(0); } while (0)
; #define PG8_WAIT_V(n) asm volatile("s_waitcnt vmcnt(" #n ")" ::: "memory")
; template <class Epi, class Sched, bool ALIGN_EPI = false, bool SP2 = false>
; __device__ __forceinline__ void gemm_phase(PG8_LAS unsigned char* lds, const Gemm g, const Sched& S, const Epi& E) {
;     ...
;             PG8_LDB(B0, 0, 0); PG8_LDB(B1, 0, 1); PG8_SCHED; PG8_LDA(At, 0, 0); PG8_STAGE(PG8_SA(1, 1), a1 + hstep, voffA);
;             PG8_WAIT_V(8); PG8_WAIT_L(0); PG8_BAR; PG8_MMA(0, 0, At, B0); PG8_MMA(0, 1, At, B1); PG8_BAR; PG8_SCHED;
;             PG8_LDA(At, 0, 1); PG8_STAGE(PG8_SB(0, 0), b2, voffB); PG8_STAGE(PG8_SB(0, 1), b2 + hstep, voffB); PG8_STAGE(PG8_SA(0, 0), a2, voffA);
;             PG8_WAIT_V(8); PG8_WAIT_L(0); PG8_BAR; PG8_MMA(1, 0, At, B0); PG8_MMA(1, 1, At, B1); PG8_BAR; PG8_SCHED;
;             PG8_LDB(B0, 1, 0); PG8_LDB(B1, 1, 1); PG8_SCHED; PG8_LDA(At, 1, 0); PG8_STAGE(PG8_SA(0, 1), a2 + hstep, voffA);
;             PG8_WAIT_V(8); PG8_WAIT_L(0); PG8_BAR; PG8_MMA(0, 0, At, B0); PG8_MMA(0, 1, At, B1); PG8_BAR; PG8_SCHED;
;             PG8_LDA(At, 1, 1); PG8_STAGE(PG8_SB(1, 0), b3, voffB); PG8_STAGE(PG8_SB(1, 1), b3 + hstep, voffB); PG8_STAGE(PG8_SA(1, 0), a3, voffA);
;             PG8_WAIT_V(8); PG8_WAIT_L(0); PG8_BAR; PG8_MMA(1, 0, At, B0); PG8_MMA(1, 1, At, B1); PG8_BAR; PG8_SCHED;
	s_add_i32 s4, s84, s80
	v_lshl_add_u64 v[206:207], v[206:207], 0, s[98:99]
	s_mov_b32 m0, s4
	ds_read_b128 v[162:165], v249 offset:49152
	ds_read_b128 v[166:169], v249 offset:50176
	ds_read_b128 v[170:173], v249 offset:51200
	ds_read_b128 v[174:177], v249 offset:52224
	ds_read_b128 v[178:181], v249 offset:53248
	ds_read_b128 v[182:185], v249 offset:54272
	ds_read_b128 v[186:189], v249 offset:55296
	ds_read_b128 v[190:193], v249 offset:56320
	global_load_lds_dwordx4 v[206:207], off
	v_lshl_add_u64 v[206:207], v[212:213], 0, s[98:99]
	s_add_i32 m0, s4, 0x2000
	s_add_i32 s4, vcc_hi, s80
	global_load_lds_dwordx4 v[206:207], off
	v_lshl_add_u64 v[206:207], v[214:215], 0, s[98:99]
	s_mov_b32 m0, s4
	s_nop 0
	global_load_lds_dwordx4 v[206:207], off
	v_lshl_add_u64 v[206:207], v[216:217], 0, s[98:99]
	s_add_i32 m0, s4, 0x2000
	s_nop 0
	global_load_lds_dwordx4 v[206:207], off
	v_lshl_add_u64 v[206:207], v[218:219], 0, s[98:99]
	s_mov_b32 m0, s10
	s_nop 0
	global_load_lds_dwordx4 v[206:207], off
	v_lshl_add_u64 v[206:207], v[220:221], 0, s[98:99]
	s_mov_b32 m0, s11
	s_nop 0
	global_load_lds_dwordx4 v[206:207], off
	s_waitcnt vmcnt(8)
	s_waitcnt lgkmcnt(0)
	s_barrier
	s_setprio 1
	s_waitcnt lgkmcnt(0)
	v_mfma_f32_16x16x32_bf16 v[62:65], v[98:101], v[162:165], v[62:65]
	v_mfma_f32_16x16x32_bf16 v[58:61], v[114:117], v[162:165], v[58:61]
	v_mfma_f32_16x16x32_bf16 v[42:45], v[114:117], v[170:173], v[42:45]
	v_mfma_f32_16x16x32_bf16 v[46:49], v[98:101], v[170:173], v[46:49]
	v_mfma_f32_16x16x32_bf16 v[30:33], v[98:101], v[178:181], v[30:33]
	v_mfma_f32_16x16x32_bf16 v[26:29], v[114:117], v[178:181], v[26:29]
	v_mfma_f32_16x16x32_bf16 v[10:13], v[114:117], v[186:189], v[10:13]
	v_mfma_f32_16x16x32_bf16 v[14:17], v[98:101], v[186:189], v[14:17]
	v_mfma_f32_16x16x32_bf16 v[62:65], v[102:105], v[166:169], v[62:65]
	v_mfma_f32_16x16x32_bf16 v[58:61], v[122:125], v[166:169], v[58:61]
	v_mfma_f32_16x16x32_bf16 v[42:45], v[122:125], v[174:177], v[42:45]
	v_mfma_f32_16x16x32_bf16 v[46:49], v[102:105], v[174:177], v[46:49]
	v_mfma_f32_16x16x32_bf16 v[30:33], v[102:105], v[182:185], v[30:33]
	v_mfma_f32_16x16x32_bf16 v[26:29], v[122:125], v[182:185], v[26:29]
	v_mfma_f32_16x16x32_bf16 v[10:13], v[122:125], v[190:193], v[10:13]
	v_mfma_f32_16x16x32_bf16 v[14:17], v[102:105], v[190:193], v[14:17]
	s_setprio 0
	s_setprio 1
	v_mfma_f32_16x16x32_bf16 v[54:57], v[130:133], v[162:165], v[54:57]
	v_mfma_f32_16x16x32_bf16 v[50:53], v[146:149], v[162:165], v[50:53]
	v_mfma_f32_16x16x32_bf16 v[34:37], v[146:149], v[170:173], v[34:37]
	v_mfma_f32_16x16x32_bf16 v[38:41], v[130:133], v[170:173], v[38:41]
	v_mfma_f32_16x16x32_bf16 v[22:25], v[130:133], v[178:181], v[22:25]
	v_mfma_f32_16x16x32_bf16 v[18:21], v[146:149], v[178:181], v[18:21]
	v_mfma_f32_16x16x32_bf16 v[2:5], v[146:149], v[186:189], v[2:5]
	v_mfma_f32_16x16x32_bf16 v[6:9], v[130:133], v[186:189], v[6:9]
	v_mfma_f32_16x16x32_bf16 v[54:57], v[138:141], v[166:169], v[54:57]
	v_mfma_f32_16x16x32_bf16 v[50:53], v[154:157], v[166:169], v[50:53]
	v_mfma_f32_16x16x32_bf16 v[34:37], v[154:157], v[174:177], v[34:37]
	v_mfma_f32_16x16x32_bf16 v[38:41], v[138:141], v[174:177], v[38:41]
	v_mfma_f32_16x16x32_bf16 v[22:25], v[138:141], v[182:185], v[22:25]
	v_mfma_f32_16x16x32_bf16 v[18:21], v[154:157], v[182:185], v[18:21]
	v_mfma_f32_16x16x32_bf16 v[2:5], v[154:157], v[190:193], v[2:5]
	v_mfma_f32_16x16x32_bf16 v[6:9], v[138:141], v[190:193], v[6:9]
	s_setprio 0
	s_barrier
	s_add_u32 s6, s6, s98
	s_addc_u32 s7, s7, 0
	s_add_u32 s6, s6, s98
	s_addc_u32 s7, s7, 0
	s_add_u32 s67, s67, s98
	s_addc_u32 s85, s85, 0
	s_add_u32 s67, s67, s98
	s_addc_u32 s85, s85, 0
	s_cmp_ge_u32 vcc_lo, s69
	s_mov_b32 s8, vcc_lo
	s_cbranch_scc0 .LBB0_175
	s_branch .Lpeelx175
.LBB0_175:
	s_add_i32 vcc_lo, s8, 2
	s_add_u32 s4, s6, s98
	s_addc_u32 s5, s7, 0
	s_add_i32 vcc_hi, 0, 0x10000
	s_cmp_eq_u32 s13, s8
	s_cselect_b32 s9, s1, s5
	s_cselect_b32 s8, s0, s4
	s_cselect_b32 s5, s97, s85
	s_cselect_b32 s4, s96, s67
	s_add_i32 s84, 0, 0x14000
	v_add_u32_e32 v122, vcc_hi, v248
	v_add_u32_e32 v154, s84, v248
	ds_read_b128 v[98:101], v122
	ds_read_b128 v[102:105], v122 offset:1024
	ds_read_b128 v[114:117], v122 offset:2048
	ds_read_b128 v[122:125], v122 offset:3072
	ds_read_b128 v[130:133], v154
	ds_read_b128 v[138:141], v154 offset:1024
	ds_read_b128 v[146:149], v154 offset:2048
	ds_read_b128 v[154:157], v154 offset:3072
	v_lshl_add_u64 v[206:207], s[6:7], 0, v[200:201]
	s_add_i32 m0, s81, 0xc000
	ds_read_b128 v[162:165], v249
	ds_read_b128 v[166:169], v249 offset:1024
	ds_read_b128 v[170:173], v249 offset:2048
	ds_read_b128 v[174:177], v249 offset:3072
	ds_read_b128 v[178:181], v249 offset:4096
	ds_read_b128 v[182:185], v249 offset:5120
	ds_read_b128 v[186:189], v249 offset:6144
	ds_read_b128 v[190:193], v249 offset:7168
	global_load_lds_dwordx4 v[206:207], off
	v_lshl_add_u64 v[206:207], s[6:7], 0, v[210:211]
	s_add_i32 m0, s81, 0xe000
	s_nop 0
	global_load_lds_dwordx4 v[206:207], off
	s_waitcnt vmcnt(8)
	s_waitcnt lgkmcnt(0)
	s_barrier
; #define PG8_STAGE(bufoff, gbase, voff) do { _Pragma("unroll") for (int _i = 0; _i < 2; ++_i) \
;         __builtin_amdgcn_global_load_lds((const unsigned*)((const char*)(gbase) + (voff)[_i]), (PG8_LAS unsigned*)(lds + (bufoff) + ldsw + _i * 8192), 16, 0, 0); } while (0)
; #define PG8_LDA(dst, b, h) do { _Pragma("unroll") for (int m = 0; m < 4; ++m) _Pragma("unroll") for (int k = 0; k < 2; ++k) dst[m][k] = *(const PG8_LAS bf16x8*)(lds + PG8_SA(b, h) + aoff + m * 2048 + k * 1024); } while (0)
; #define PG8_MMA(ai, bj, At, Bt) do { __builtin_amdgcn_s_setprio(1); _Pragma("unroll") for (int m = 0; m < 4; ++m) _Pragma("unroll") for (int n = 0; n < 2; ++n) _Pragma("unroll") for (int k = 0; k < 2; ++k) \
;         acc[ai][bj][m][n] = mma16<Epi::I8>(Bt[n][k], At[m][k], acc[ai][bj][m][n]); __builtin_amdgcn_s_setprio(0); } while (0)
; #define PG8_WAIT_V(n) asm volatile("s_waitcnt vmcnt(" #n ")" ::: "memory")
; #define PG8_WAIT_L(n) asm volatile("s_waitcnt lgkmcnt(" #n ")" ::: "memory")
; #define PG8_BAR __builtin_amdgcn_s_barrier()
; #define PG8_SCHED __builtin_amdgcn_sched_barrier(0)
; template <class Epi, class Sched, bool ALIGN_EPI = false, bool SP2 = false>
; __device__ __forceinline__ void gemm_phase(PG8_LAS unsigned char* lds, const Gemm g, const Sched& S, const Epi& E) {
;     ...
;             PG8_WAIT_V(8); PG8_WAIT_L(0); PG8_BAR; PG8_MMA(0, 0, At, B0); PG8_MMA(0, 1, At, B1); PG8_BAR; PG8_SCHED;
;             PG8_LDA(At, 0, 1); PG8_STAGE(PG8_SB(0, 0), b2, voffB); PG8_STAGE(PG8_SB(0, 1), b2 + hstep, voffB); PG8_STAGE(PG8_SA(0, 0), a2, voffA);
;             PG8_WAIT_V(8); PG8_WAIT_L(0); PG8_BAR; PG8_MMA(1, 0, At, B0); PG8_MMA(1, 1, At, B1); PG8_BAR; PG8_SCHED;
	s_setprio 1
	s_waitcnt lgkmcnt(0)
	v_mfma_f32_16x16x32_bf16 v[158:161], v[98:101], v[162:165], v[158:161]
	v_mfma_f32_16x16x32_bf16 v[150:153], v[114:117], v[162:165], v[150:153]
	v_mfma_f32_16x16x32_bf16 v[118:121], v[114:117], v[170:173], v[118:121]
	v_mfma_f32_16x16x32_bf16 v[126:129], v[98:101], v[170:173], v[126:129]
	v_mfma_f32_16x16x32_bf16 v[94:97], v[98:101], v[178:181], v[94:97]
	v_mfma_f32_16x16x32_bf16 v[90:93], v[114:117], v[178:181], v[90:93]
	v_mfma_f32_16x16x32_bf16 v[74:77], v[114:117], v[186:189], v[74:77]
	v_mfma_f32_16x16x32_bf16 v[78:81], v[98:101], v[186:189], v[78:81]
	v_mfma_f32_16x16x32_bf16 v[158:161], v[102:105], v[166:169], v[158:161]
	v_mfma_f32_16x16x32_bf16 v[150:153], v[122:125], v[166:169], v[150:153]
	v_mfma_f32_16x16x32_bf16 v[118:121], v[122:125], v[174:177], v[118:121]
	v_mfma_f32_16x16x32_bf16 v[126:129], v[102:105], v[174:177], v[126:129]
	v_mfma_f32_16x16x32_bf16 v[94:97], v[102:105], v[182:185], v[94:97]
	v_mfma_f32_16x16x32_bf16 v[90:93], v[122:125], v[182:185], v[90:93]
	v_mfma_f32_16x16x32_bf16 v[74:77], v[122:125], v[190:193], v[74:77]
	v_mfma_f32_16x16x32_bf16 v[78:81], v[102:105], v[190:193], v[78:81]
	s_setprio 0
	s_setprio 1
	v_mfma_f32_16x16x32_bf16 v[142:145], v[130:133], v[162:165], v[142:145]
	v_mfma_f32_16x16x32_bf16 v[134:137], v[146:149], v[162:165], v[134:137]
	v_mfma_f32_16x16x32_bf16 v[106:109], v[146:149], v[170:173], v[106:109]
	v_mfma_f32_16x16x32_bf16 v[110:113], v[130:133], v[170:173], v[110:113]
	v_mfma_f32_16x16x32_bf16 v[86:89], v[130:133], v[178:181], v[86:89]
	v_mfma_f32_16x16x32_bf16 v[82:85], v[146:149], v[178:181], v[82:85]
	v_mfma_f32_16x16x32_bf16 v[66:69], v[146:149], v[186:189], v[66:69]
	v_mfma_f32_16x16x32_bf16 v[70:73], v[130:133], v[186:189], v[70:73]
	v_mfma_f32_16x16x32_bf16 v[142:145], v[138:141], v[166:169], v[142:145]
	v_mfma_f32_16x16x32_bf16 v[134:137], v[154:157], v[166:169], v[134:137]
	v_mfma_f32_16x16x32_bf16 v[106:109], v[154:157], v[174:177], v[106:109]
	v_mfma_f32_16x16x32_bf16 v[110:113], v[138:141], v[174:177], v[110:113]
	v_mfma_f32_16x16x32_bf16 v[86:89], v[138:141], v[182:185], v[86:89]
	v_mfma_f32_16x16x32_bf16 v[82:85], v[154:157], v[182:185], v[82:85]
	v_mfma_f32_16x16x32_bf16 v[66:69], v[154:157], v[190:193], v[66:69]
	v_mfma_f32_16x16x32_bf16 v[70:73], v[138:141], v[190:193], v[70:73]
	s_setprio 0
	s_barrier
	s_add_i32 vcc_hi, vcc_hi, s80
	v_lshl_add_u64 v[206:207], s[4:5], 0, v[0:1]
	s_mov_b32 m0, vcc_hi
	ds_read_b128 v[162:165], v249 offset:16384
	ds_read_b128 v[166:169], v249 offset:17408
	ds_read_b128 v[170:173], v249 offset:18432
	ds_read_b128 v[174:177], v249 offset:19456
	ds_read_b128 v[178:181], v249 offset:20480
	ds_read_b128 v[182:185], v249 offset:21504
	ds_read_b128 v[186:189], v249 offset:22528
	ds_read_b128 v[190:193], v249 offset:23552
	global_load_lds_dwordx4 v[206:207], off
	s_add_i32 m0, vcc_hi, 0x2000
	v_lshl_add_u64 v[212:213], s[4:5], 0, v[198:199]
	s_add_u32 s4, s4, s100
	s_addc_u32 s5, s5, 0
	s_add_i32 s84, s84, s80
	global_load_lds_dwordx4 v[212:213], off
	v_lshl_add_u64 v[214:215], s[4:5], 0, v[0:1]
	s_mov_b32 m0, s84
	v_lshl_add_u64 v[216:217], s[4:5], 0, v[198:199]
	global_load_lds_dwordx4 v[214:215], off
	s_add_i32 m0, s84, 0x2000
	v_lshl_add_u64 v[218:219], s[8:9], 0, v[194:195]
	global_load_lds_dwordx4 v[216:217], off
	s_mov_b32 m0, s81
	v_lshl_add_u64 v[220:221], s[8:9], 0, v[196:197]
	global_load_lds_dwordx4 v[218:219], off
	s_mov_b32 m0, s70
	s_nop 0
	global_load_lds_dwordx4 v[220:221], off
	s_waitcnt vmcnt(8)
	s_waitcnt lgkmcnt(0)
	s_barrier
	s_setprio 1
	s_waitcnt lgkmcnt(0)
	v_mfma_f32_16x16x32_bf16 v[62:65], v[98:101], v[162:165], v[62:65]
	v_mfma_f32_16x16x32_bf16 v[58:61], v[114:117], v[162:165], v[58:61]
	v_mfma_f32_16x16x32_bf16 v[42:45], v[114:117], v[170:173], v[42:45]
	v_mfma_f32_16x16x32_bf16 v[46:49], v[98:101], v[170:173], v[46:49]
	v_mfma_f32_16x16x32_bf16 v[30:33], v[98:101], v[178:181], v[30:33]
	v_mfma_f32_16x16x32_bf16 v[26:29], v[114:117], v[178:181], v[26:29]
	v_mfma_f32_16x16x32_bf16 v[10:13], v[114:117], v[186:189], v[10:13]
	v_mfma_f32_16x16x32_bf16 v[14:17], v[98:101], v[186:189], v[14:17]
	v_mfma_f32_16x16x32_bf16 v[62:65], v[102:105], v[166:169], v[62:65]
	v_mfma_f32_16x16x32_bf16 v[58:61], v[122:125], v[166:169], v[58:61]
	v_mfma_f32_16x16x32_bf16 v[42:45], v[122:125], v[174:177], v[42:45]
	v_mfma_f32_16x16x32_bf16 v[46:49], v[102:105], v[174:177], v[46:49]
	v_mfma_f32_16x16x32_bf16 v[30:33], v[102:105], v[182:185], v[30:33]
	v_mfma_f32_16x16x32_bf16 v[26:29], v[122:125], v[182:185], v[26:29]
	v_mfma_f32_16x16x32_bf16 v[10:13], v[122:125], v[190:193], v[10:13]
	v_mfma_f32_16x16x32_bf16 v[14:17], v[102:105], v[190:193], v[14:17]
	s_setprio 0
	s_setprio 1
	v_mfma_f32_16x16x32_bf16 v[54:57], v[130:133], v[162:165], v[54:57]
	v_mfma_f32_16x16x32_bf16 v[50:53], v[146:149], v[162:165], v[50:53]
	v_mfma_f32_16x16x32_bf16 v[34:37], v[146:149], v[170:173], v[34:37]
	v_mfma_f32_16x16x32_bf16 v[38:41], v[130:133], v[170:173], v[38:41]
	v_mfma_f32_16x16x32_bf16 v[22:25], v[130:133], v[178:181], v[22:25]
	v_mfma_f32_16x16x32_bf16 v[18:21], v[146:149], v[178:181], v[18:21]
	v_mfma_f32_16x16x32_bf16 v[2:5], v[146:149], v[186:189], v[2:5]
	v_mfma_f32_16x16x32_bf16 v[6:9], v[130:133], v[186:189], v[6:9]
	v_mfma_f32_16x16x32_bf16 v[54:57], v[138:141], v[166:169], v[54:57]
	v_mfma_f32_16x16x32_bf16 v[50:53], v[154:157], v[166:169], v[50:53]
	v_mfma_f32_16x16x32_bf16 v[34:37], v[154:157], v[174:177], v[34:37]
	v_mfma_f32_16x16x32_bf16 v[38:41], v[138:141], v[174:177], v[38:41]
	v_mfma_f32_16x16x32_bf16 v[22:25], v[138:141], v[182:185], v[22:25]
	v_mfma_f32_16x16x32_bf16 v[18:21], v[154:157], v[182:185], v[18:21]
	v_mfma_f32_16x16x32_bf16 v[2:5], v[154:157], v[190:193], v[2:5]
	v_mfma_f32_16x16x32_bf16 v[6:9], v[138:141], v[190:193], v[6:9]
	s_setprio 0
	s_barrier
; #define PG8_STAGE(bufoff, gbase, voff) do { _Pragma("unroll") for (int _i = 0; _i < 2; ++_i) \
;         __builtin_amdgcn_global_load_lds((const unsigned*)((const char*)(gbase) + (voff)[_i]), (PG8_LAS unsigned*)(lds + (bufoff) + ldsw + _i * 8192), 16, 0, 0); } while (0)
; #define PG8_LDA(dst, b, h) do { _Pragma("unroll") for (int m = 0; m < 4; ++m) _Pragma("unroll") for (int k = 0; k < 2; ++k) dst[m][k] = *(const PG8_LAS bf16x8*)(lds + PG8_SA(b, h) + aoff + m * 2048 + k * 1024); } while (0)
; #define PG8_LDB(dst, b, h) do { _Pragma("unroll") for (int n = 0; n < 2; ++n) _Pragma("unroll") for (int k = 0; k < 2; ++k) dst[n][k] = *(const PG8_LAS bf16x8*)(lds + PG8_SB(b, h) + boff + n * 2048 + k * 1024); } while (0)
; #define PG8_MMA(ai, bj, At, Bt) do { __builtin_amdgcn_s_setprio(1); _Pragma("unroll") for (int m = 0; m < 4; ++m) _Pragma("unroll") for (int n = 0; n < 2; ++n) _Pragma("unroll") for (int k = 0; k < 2; ++k) \
;         acc[ai][bj][m][n] = mma16<Epi::I8>(Bt[n][k], At[m][k], acc[ai][bj][m][n]); __builtin_amdgcn_s_setprio(0); } while (0)
; #define PG8_WAIT_V(n) asm volatile("s_waitcnt vmcnt(" #n ")" ::: "memory")
; #define PG8_WAIT_L(n) asm volatile("s_waitcnt lgkmcnt(" #n ")" ::: "memory")
; #define PG8_BAR __builtin_amdgcn_s_barrier()
; #define PG8_SCHED __builtin_amdgcn_sched_barrier(0)
; template <class Epi, class Sched, bool ALIGN_EPI = false, bool SP2 = false>
; __device__ __forceinline__ void gemm_phase(PG8_LAS unsigned char* lds, const Gemm g, const Sched& S, const Epi& E) {
;     ...
;             PG8_LDB(B0, 1, 0); PG8_LDB(B1, 1, 1); PG8_SCHED; PG8_LDA(At, 1, 0); PG8_STAGE(PG8_SA(0, 1), a2 + hstep, voffA);
;             PG8_WAIT_V(8); PG8_WAIT_L(0); PG8_BAR; PG8_MMA(0, 0, At, B0); PG8_MMA(0, 1, At, B1); PG8_BAR; PG8_SCHED;
	s_add_i32 s84, 0, 0x18000
	s_add_i32 vcc_hi, 0, 0x1c000
	v_add_u32_e32 v122, s84, v248
	v_add_u32_e32 v154, vcc_hi, v248
	ds_read_b128 v[98:101], v122
	ds_read_b128 v[102:105], v122 offset:1024
	ds_read_b128 v[114:117], v122 offset:2048
	ds_read_b128 v[122:125], v122 offset:3072
	ds_read_b128 v[130:133], v154
	ds_read_b128 v[138:141], v154 offset:1024
	ds_read_b128 v[146:149], v154 offset:2048
	ds_read_b128 v[154:157], v154 offset:3072
	s_add_u32 s4, s8, s100
	s_addc_u32 s5, s9, 0
	s_mov_b32 m0, s71
	v_lshl_add_u64 v[222:223], s[4:5], 0, v[194:195]
	ds_read_b128 v[162:165], v249 offset:32768
	ds_read_b128 v[166:169], v249 offset:33792
	ds_read_b128 v[170:173], v249 offset:34816
	ds_read_b128 v[174:177], v249 offset:35840
	ds_read_b128 v[178:181], v249 offset:36864
	ds_read_b128 v[182:185], v249 offset:37888
	ds_read_b128 v[186:189], v249 offset:38912
	ds_read_b128 v[190:193], v249 offset:39936
	global_load_lds_dwordx4 v[222:223], off
	v_lshl_add_u64 v[222:223], s[4:5], 0, v[196:197]
	s_mov_b32 m0, s12
	s_nop 0
	global_load_lds_dwordx4 v[222:223], off
	s_waitcnt vmcnt(8)
	s_waitcnt lgkmcnt(0)
	s_barrier
	s_setprio 1
	s_waitcnt lgkmcnt(0)
	v_mfma_f32_16x16x32_bf16 v[158:161], v[98:101], v[162:165], v[158:161]
	v_mfma_f32_16x16x32_bf16 v[150:153], v[114:117], v[162:165], v[150:153]
	v_mfma_f32_16x16x32_bf16 v[118:121], v[114:117], v[170:173], v[118:121]
	v_mfma_f32_16x16x32_bf16 v[126:129], v[98:101], v[170:173], v[126:129]
	v_mfma_f32_16x16x32_bf16 v[94:97], v[98:101], v[178:181], v[94:97]
	v_mfma_f32_16x16x32_bf16 v[90:93], v[114:117], v[178:181], v[90:93]
	v_mfma_f32_16x16x32_bf16 v[74:77], v[114:117], v[186:189], v[74:77]
	v_mfma_f32_16x16x32_bf16 v[78:81], v[98:101], v[186:189], v[78:81]
	v_mfma_f32_16x16x32_bf16 v[158:161], v[102:105], v[166:169], v[158:161]
	v_mfma_f32_16x16x32_bf16 v[150:153], v[122:125], v[166:169], v[150:153]
	v_mfma_f32_16x16x32_bf16 v[118:121], v[122:125], v[174:177], v[118:121]
	v_mfma_f32_16x16x32_bf16 v[126:129], v[102:105], v[174:177], v[126:129]
	v_mfma_f32_16x16x32_bf16 v[94:97], v[102:105], v[182:185], v[94:97]
	v_mfma_f32_16x16x32_bf16 v[90:93], v[122:125], v[182:185], v[90:93]
	v_mfma_f32_16x16x32_bf16 v[74:77], v[122:125], v[190:193], v[74:77]
	v_mfma_f32_16x16x32_bf16 v[78:81], v[102:105], v[190:193], v[78:81]
	s_setprio 0
	s_setprio 1
	v_mfma_f32_16x16x32_bf16 v[142:145], v[130:133], v[162:165], v[142:145]
	v_mfma_f32_16x16x32_bf16 v[134:137], v[146:149], v[162:165], v[134:137]
	v_mfma_f32_16x16x32_bf16 v[106:109], v[146:149], v[170:173], v[106:109]
	v_mfma_f32_16x16x32_bf16 v[110:113], v[130:133], v[170:173], v[110:113]
	v_mfma_f32_16x16x32_bf16 v[86:89], v[130:133], v[178:181], v[86:89]
	v_mfma_f32_16x16x32_bf16 v[82:85], v[146:149], v[178:181], v[82:85]
	v_mfma_f32_16x16x32_bf16 v[66:69], v[146:149], v[186:189], v[66:69]
	v_mfma_f32_16x16x32_bf16 v[70:73], v[130:133], v[186:189], v[70:73]
	v_mfma_f32_16x16x32_bf16 v[142:145], v[138:141], v[166:169], v[142:145]
	v_mfma_f32_16x16x32_bf16 v[134:137], v[154:157], v[166:169], v[134:137]
	v_mfma_f32_16x16x32_bf16 v[106:109], v[154:157], v[174:177], v[106:109]
	v_mfma_f32_16x16x32_bf16 v[110:113], v[138:141], v[174:177], v[110:113]
	v_mfma_f32_16x16x32_bf16 v[86:89], v[138:141], v[182:185], v[86:89]
	v_mfma_f32_16x16x32_bf16 v[82:85], v[154:157], v[182:185], v[82:85]
	v_mfma_f32_16x16x32_bf16 v[66:69], v[154:157], v[190:193], v[66:69]
	v_mfma_f32_16x16x32_bf16 v[70:73], v[138:141], v[190:193], v[70:73]
	s_setprio 0
	s_barrier
; #define PG8_STAGE(bufoff, gbase, voff) do { _Pragma("unroll") for (int _i = 0; _i < 2; ++_i) \
;         __builtin_amdgcn_global_load_lds((const unsigned*)((const char*)(gbase) + (voff)[_i]), (PG8_LAS unsigned*)(lds + (bufoff) + ldsw + _i * 8192), 16, 0, 0); } while (0)
; #define PG8_LDA(dst, b, h) do { _Pragma("unroll") for (int m = 0; m < 4; ++m) _Pragma("unroll") for (int k = 0; k < 2; ++k) dst[m][k] = *(const PG8_LAS bf16x8*)(lds + PG8_SA(b, h) + aoff + m * 2048 + k * 1024); } while (0)
; #define PG8_MMA(ai, bj, At, Bt) do { __builtin_amdgcn_s_setprio(1); _Pragma("unroll") for (int m = 0; m < 4; ++m) _Pragma("unroll") for (int n = 0; n < 2; ++n) _Pragma("unroll") for (int k = 0; k < 2; ++k) \
;         acc[ai][bj][m][n] = mma16<Epi::I8>(Bt[n][k], At[m][k], acc[ai][bj][m][n]); __builtin_amdgcn_s_setprio(0); } while (0)
; #define PG8_WAIT_V(n) asm volatile("s_waitcnt vmcnt(" #n ")" ::: "memory")
; #define PG8_WAIT_L(n) asm volatile("s_waitcnt lgkmcnt(" #n ")" ::: "memory")
; #define PG8_BAR __builtin_amdgcn_s_barrier()
; #define PG8_SCHED __builtin_amdgcn_sched_barrier(0)
; template <class Epi, class Sched, bool ALIGN_EPI = false, bool SP2 = false>
; __device__ __forceinline__ void gemm_phase(PG8_LAS unsigned char* lds, const Gemm g, const Sched& S, const Epi& E) {
;     ...
;         for (int t = 0; t < nt; t += 2) {
;             const bool last = (t == nt - 2);
;             const char* a1 = cA + (size_t)(t + 1) * kstep;
;             const char* a2 = last ? nA : cA + (size_t)(t + 2) * kstep; const char* b2 = last ? nB : cB + (size_t)(t + 2) * kstep;
;     ...
;             PG8_LDA(At, 1, 1); PG8_STAGE(PG8_SB(1, 0), b3, voffB); PG8_STAGE(PG8_SB(1, 1), b3 + hstep, voffB); PG8_STAGE(PG8_SA(1, 0), a3, voffA);
;             PG8_WAIT_V(8); PG8_WAIT_L(0); PG8_BAR; PG8_MMA(1, 0, At, B0); PG8_MMA(1, 1, At, B1); PG8_BAR; PG8_SCHED;
	s_add_i32 s4, s84, s80
	v_lshl_add_u64 v[206:207], v[206:207], 0, s[98:99]
	s_mov_b32 m0, s4
	ds_read_b128 v[162:165], v249 offset:49152
	ds_read_b128 v[166:169], v249 offset:50176
	ds_read_b128 v[170:173], v249 offset:51200
	ds_read_b128 v[174:177], v249 offset:52224
	ds_read_b128 v[178:181], v249 offset:53248
	ds_read_b128 v[182:185], v249 offset:54272
	ds_read_b128 v[186:189], v249 offset:55296
	ds_read_b128 v[190:193], v249 offset:56320
	global_load_lds_dwordx4 v[206:207], off
	v_lshl_add_u64 v[206:207], v[212:213], 0, s[98:99]
	s_add_i32 m0, s4, 0x2000
	s_add_i32 s4, vcc_hi, s80
	global_load_lds_dwordx4 v[206:207], off
	v_lshl_add_u64 v[206:207], v[214:215], 0, s[98:99]
	s_mov_b32 m0, s4
	s_nop 0
	global_load_lds_dwordx4 v[206:207], off
	v_lshl_add_u64 v[206:207], v[216:217], 0, s[98:99]
	s_add_i32 m0, s4, 0x2000
	s_nop 0
	global_load_lds_dwordx4 v[206:207], off
	v_lshl_add_u64 v[206:207], v[218:219], 0, s[98:99]
	s_mov_b32 m0, s10
	s_nop 0
	global_load_lds_dwordx4 v[206:207], off
	v_lshl_add_u64 v[206:207], v[220:221], 0, s[98:99]
	s_mov_b32 m0, s11
	s_nop 0
	global_load_lds_dwordx4 v[206:207], off
	s_waitcnt vmcnt(8)
	s_waitcnt lgkmcnt(0)
	s_barrier
	s_setprio 1
	s_waitcnt lgkmcnt(0)
	v_mfma_f32_16x16x32_bf16 v[62:65], v[98:101], v[162:165], v[62:65]
	v_mfma_f32_16x16x32_bf16 v[58:61], v[114:117], v[162:165], v[58:61]
	v_mfma_f32_16x16x32_bf16 v[42:45], v[114:117], v[170:173], v[42:45]
	v_mfma_f32_16x16x32_bf16 v[46:49], v[98:101], v[170:173], v[46:49]
	v_mfma_f32_16x16x32_bf16 v[30:33], v[98:101], v[178:181], v[30:33]
	v_mfma_f32_16x16x32_bf16 v[26:29], v[114:117], v[178:181], v[26:29]
	v_mfma_f32_16x16x32_bf16 v[10:13], v[114:117], v[186:189], v[10:13]
	v_mfma_f32_16x16x32_bf16 v[14:17], v[98:101], v[186:189], v[14:17]
	v_mfma_f32_16x16x32_bf16 v[62:65], v[102:105], v[166:169], v[62:65]
	v_mfma_f32_16x16x32_bf16 v[58:61], v[122:125], v[166:169], v[58:61]
	v_mfma_f32_16x16x32_bf16 v[42:45], v[122:125], v[174:177], v[42:45]
	v_mfma_f32_16x16x32_bf16 v[46:49], v[102:105], v[174:177], v[46:49]
	v_mfma_f32_16x16x32_bf16 v[30:33], v[102:105], v[182:185], v[30:33]
	v_mfma_f32_16x16x32_bf16 v[26:29], v[122:125], v[182:185], v[26:29]
	v_mfma_f32_16x16x32_bf16 v[10:13], v[122:125], v[190:193], v[10:13]
	v_mfma_f32_16x16x32_bf16 v[14:17], v[102:105], v[190:193], v[14:17]
	s_setprio 0
	s_setprio 1
	v_mfma_f32_16x16x32_bf16 v[54:57], v[130:133], v[162:165], v[54:57]
	v_mfma_f32_16x16x32_bf16 v[50:53], v[146:149], v[162:165], v[50:53]
	v_mfma_f32_16x16x32_bf16 v[34:37], v[146:149], v[170:173], v[34:37]
	v_mfma_f32_16x16x32_bf16 v[38:41], v[130:133], v[170:173], v[38:41]
	v_mfma_f32_16x16x32_bf16 v[22:25], v[130:133], v[178:181], v[22:25]
	v_mfma_f32_16x16x32_bf16 v[18:21], v[146:149], v[178:181], v[18:21]
	v_mfma_f32_16x16x32_bf16 v[2:5], v[146:149], v[186:189], v[2:5]
	v_mfma_f32_16x16x32_bf16 v[6:9], v[130:133], v[186:189], v[6:9]
	v_mfma_f32_16x16x32_bf16 v[54:57], v[138:141], v[166:169], v[54:57]
	v_mfma_f32_16x16x32_bf16 v[50:53], v[154:157], v[166:169], v[50:53]
	v_mfma_f32_16x16x32_bf16 v[34:37], v[154:157], v[174:177], v[34:37]
	v_mfma_f32_16x16x32_bf16 v[38:41], v[138:141], v[174:177], v[38:41]
	v_mfma_f32_16x16x32_bf16 v[22:25], v[138:141], v[182:185], v[22:25]
	v_mfma_f32_16x16x32_bf16 v[18:21], v[154:157], v[182:185], v[18:21]
	v_mfma_f32_16x16x32_bf16 v[2:5], v[154:157], v[190:193], v[2:5]
	v_mfma_f32_16x16x32_bf16 v[6:9], v[138:141], v[190:193], v[6:9]
	s_setprio 0
	s_barrier
	s_add_u32 s6, s6, s98
	s_addc_u32 s7, s7, 0
	s_add_u32 s6, s6, s98
	s_addc_u32 s7, s7, 0
	s_add_u32 s67, s67, s98
	s_addc_u32 s85, s85, 0
	s_add_u32 s67, s67, s98
	s_addc_u32 s85, s85, 0
	s_cmp_ge_u32 vcc_lo, s69
	s_mov_b32 s8, vcc_lo
	s_cbranch_scc0 .LBB0_175

; #define LAS __attribute__((address_space(3)))
; __device__ __forceinline__ void transpose_item(const float* W, int K, int N, bf16* WT, const float* gain, LAS float* scr, int item, int lane, bool ffn_perm) {
;     const int nblk = N / 64, kb = item / nblk, nb = item % nblk, k0 = 64 * kb, n0 = 64 * nb;
;     int d0 = n0; if (ffn_perm) { const int half = n0 >= DFF, cc = n0 - half * DFF; d0 = (cc >> 7) * 256 + half * 128 + (cc & 127); }
;     const int lr = lane >> 4, lc = (lane & 15) * 4;
;     const float* src = W + (size_t)(k0 + lr) * N + n0 + lc;
;     f32x4 v[16];
; #pragma unroll
;     for (int i = 0; i < 16; ++i) v[i] = __builtin_nontemporal_load((const f32x4*)(src + (size_t)(4 * i) * N));
; #pragma unroll
;     for (int i = 0; i < 16; ++i) { LAS float* d = scr + (4 * i + lr) * 65 + lc; d[0] = v[i][0]; d[1] = v[i][1]; d[2] = v[i][2]; d[3] = v[i][3]; }
.LBB0_471:
	s_andn2_b64 vcc, exec, s[4:5]
	s_cbranch_vccnz .LBB0_463
	v_readlane_b32 s16, v252, 1
	v_mov_b32_e32 v2, 0x1600000
	v_readlane_b32 s20, v252, 5
	v_mad_u64_u32 v[70:71], s[10:11], s7, v2, v[68:69]
	v_readlane_b32 s21, v252, 6
	s_add_u32 s8, s20, s8
	s_mul_i32 s10, s6, 0x58000
	s_addc_u32 s9, s21, s9
	v_add_u32_e32 v83, s10, v82
	s_lshl_b32 s12, s6, 6
	s_lshl_b32 s13, s74, 6
	s_mov_b32 s58, s6
	v_readlane_b32 s17, v252, 2
	v_readlane_b32 s18, v252, 3
	v_readlane_b32 s19, v252, 4
	v_readlane_b32 s22, v252, 7
	v_readlane_b32 s23, v252, 8
	v_mbcnt_lo_u32_b32 v100, -1, 0
	v_mbcnt_hi_u32_b32 v100, -1, v100
	v_and_b32_e32 v101, 7, v100
	v_lshrrev_b32_e32 v100, 3, v100
	v_bfe_u32 v102, v100, 2, 1
	v_lshlrev_b32_e32 v102, 11, v102
	v_lshrrev_b32_e32 v103, 2, v101
	v_lshl_or_b32 v102, v103, 10, v102
	v_and_b32_e32 v103, 3, v100
	v_lshl_or_b32 v102, v103, 6, v102
	v_and_b32_e32 v103, 3, v101
	v_lshl_or_b32 v102, v103, 4, v102
	v_xor_b32_e32 v103, 32, v102
	v_add_u32_e32 v100, 0x1000, v102
	v_add_u32_e32 v101, 0x1000, v103
	s_mul_i32 s98, s7, 0x1600000
	s_add_u32 s98, s98, 0x10c00000
	s_add_u32 s98, s34, s98
	s_addc_u32 s99, s35, 0
.LBB0_473:
	s_lshr_b32 s100, s58, 5
	s_lshl_b32 s100, s100, 15
	s_and_b32 s101, s58, 1
	s_lshl_b32 s101, s101, 13
	s_add_u32 s100, s100, s101
	s_bfe_u32 s101, s58, 0x10001
	s_lshl_b32 s101, s101, 14
	s_add_u32 s100, s100, s101
	s_bfe_u32 s101, s58, 0x30002
	s_mul_i32 s101, s101, 0x2c0000
	s_add_u32 s100, s100, s101
	s_add_u32 s100, s98, s100
	s_addc_u32 s101, s99, 0
	s_ashr_i32 s10, s58, 31
	s_lshr_b32 s10, s10, 27
	s_add_i32 s10, s58, s10
	s_ashr_i32 s66, s10, 5
	s_lshl_b32 s10, s66, 6
	v_or_b32_e32 v2, s10, v63
	s_lshl_b32 s11, s66, 11
	v_ashrrev_i32_e32 v3, 31, v2
	s_sub_i32 s68, s12, s11
	v_lshlrev_b64 v[2:3], 13, v[2:3]
	v_lshl_add_u64 v[2:3], s[8:9], 0, v[2:3]
	s_ashr_i32 s69, s68, 31
	v_lshl_add_u64 v[2:3], s[68:69], 2, v[2:3]
	v_lshl_add_u64 v[2:3], v[2:3], 0, v[0:1]
	v_add_co_u32_e32 v4, vcc, s33, v2
	global_load_dwordx4 v[84:87], v[2:3], off nt
	s_nop 0
	v_addc_co_u32_e32 v5, vcc, 0, v3, vcc
	global_load_dwordx4 v[58:61], v[4:5], off nt
	v_add_co_u32_e32 v4, vcc, s2, v2
	s_mul_i32 s66, s66, 0xff500000
	s_nop 0
	v_addc_co_u32_e32 v5, vcc, 0, v3, vcc
	global_load_dwordx4 v[54:57], v[4:5], off nt
	v_add_co_u32_e32 v4, vcc, s73, v2
	s_ashr_i32 s11, s10, 31
	s_nop 0
	v_addc_co_u32_e32 v5, vcc, 0, v3, vcc
	global_load_dwordx4 v[50:53], v[4:5], off nt
	v_add_co_u32_e32 v4, vcc, s62, v2
	s_add_i32 s58, s58, s74
	s_nop 0
	v_addc_co_u32_e32 v5, vcc, 0, v3, vcc
	global_load_dwordx4 v[46:49], v[4:5], off nt
	v_add_co_u32_e32 v4, vcc, s55, v2
	s_add_i32 s12, s12, s13
	s_nop 0
	v_addc_co_u32_e32 v5, vcc, 0, v3, vcc
	global_load_dwordx4 v[42:45], v[4:5], off nt
	v_add_co_u32_e32 v4, vcc, s14, v2
	s_cmpk_lt_i32 s58, 0xb00
	s_nop 0
	v_addc_co_u32_e32 v5, vcc, 0, v3, vcc
	global_load_dwordx4 v[38:41], v[4:5], off nt
	v_add_co_u32_e32 v4, vcc, s56, v2
	s_nop 1
	v_addc_co_u32_e32 v5, vcc, 0, v3, vcc
	global_load_dwordx4 v[34:37], v[4:5], off nt
	v_add_co_u32_e32 v4, vcc, s61, v2
	s_nop 1
	v_addc_co_u32_e32 v5, vcc, 0, v3, vcc
	global_load_dwordx4 v[30:33], v[4:5], off nt
	v_add_co_u32_e32 v4, vcc, s60, v2
	s_nop 1
	v_addc_co_u32_e32 v5, vcc, 0, v3, vcc
	global_load_dwordx4 v[26:29], v[4:5], off nt
	v_add_co_u32_e32 v4, vcc, s90, v2
	s_nop 1
	v_addc_co_u32_e32 v5, vcc, 0, v3, vcc
	global_load_dwordx4 v[22:25], v[4:5], off nt
	v_add_co_u32_e32 v4, vcc, s57, v2
	s_nop 1
	v_addc_co_u32_e32 v5, vcc, 0, v3, vcc
	global_load_dwordx4 v[18:21], v[4:5], off nt
	v_add_co_u32_e32 v4, vcc, s91, v2
	s_nop 1
	v_addc_co_u32_e32 v5, vcc, 0, v3, vcc
	global_load_dwordx4 v[14:17], v[4:5], off nt
	v_add_co_u32_e32 v4, vcc, s3, v2
	s_nop 1
	v_addc_co_u32_e32 v5, vcc, 0, v3, vcc
	global_load_dwordx4 v[10:13], v[4:5], off nt
	v_add_co_u32_e32 v4, vcc, s52, v2
	s_nop 1
	v_addc_co_u32_e32 v5, vcc, 0, v3, vcc
	global_load_dwordx4 v[6:9], v[4:5], off nt
	v_add_co_u32_e32 v2, vcc, s76, v2
	s_nop 1
	v_addc_co_u32_e32 v3, vcc, 0, v3, vcc
	global_load_dwordx4 v[2:5], v[2:3], off nt
	s_waitcnt vmcnt(15)
	ds_write2_b32 v78, v84, v85 offset1:1
	ds_write2_b32 v78, v86, v87 offset0:2 offset1:3
	v_add_u32_e32 v84, 0x410, v78
	s_waitcnt vmcnt(14)
	ds_write2_b32 v84, v58, v59 offset1:1
	v_add_u32_e32 v58, 0x418, v78
	ds_write2_b32 v58, v60, v61 offset1:1
	v_add_u32_e32 v58, 0x820, v78
	s_waitcnt vmcnt(13)
	ds_write2_b32 v58, v54, v55 offset1:1
	v_add_u32_e32 v54, 0x828, v78
	ds_write2_b32 v54, v56, v57 offset1:1
	v_add_u32_e32 v54, 0xc30, v78
	s_waitcnt vmcnt(12)
	ds_write2_b32 v54, v50, v51 offset1:1
	v_add_u32_e32 v50, 0xc38, v78
	ds_write2_b32 v50, v52, v53 offset1:1
	v_add_u32_e32 v50, 0x1040, v78
	s_waitcnt vmcnt(11)
	ds_write2_b32 v50, v46, v47 offset1:1
	v_add_u32_e32 v46, 0x1048, v78
	ds_write2_b32 v46, v48, v49 offset1:1
	v_add_u32_e32 v46, 0x1450, v78
	s_waitcnt vmcnt(10)
	ds_write2_b32 v46, v42, v43 offset1:1
	v_add_u32_e32 v42, 0x1458, v78
	ds_write2_b32 v42, v44, v45 offset1:1
	v_add_u32_e32 v42, 0x1860, v78
	s_waitcnt vmcnt(9)
	ds_write2_b32 v42, v38, v39 offset1:1
	v_add_u32_e32 v38, 0x1868, v78
	ds_write2_b32 v38, v40, v41 offset1:1
	v_add_u32_e32 v38, 0x1c70, v78
	s_waitcnt vmcnt(8)
	ds_write2_b32 v38, v34, v35 offset1:1
	v_add_u32_e32 v34, 0x1c78, v78
	ds_write2_b32 v34, v36, v37 offset1:1
	v_add_u32_e32 v34, 0x2080, v78
	s_waitcnt vmcnt(7)
	ds_write2_b32 v34, v30, v31 offset1:1
	v_add_u32_e32 v30, 0x2088, v78
	ds_write2_b32 v30, v32, v33 offset1:1
	v_add_u32_e32 v30, 0x2490, v78
	s_waitcnt vmcnt(6)
	ds_write2_b32 v30, v26, v27 offset1:1
	v_add_u32_e32 v26, 0x2498, v78
	ds_write2_b32 v26, v28, v29 offset1:1
	v_add_u32_e32 v26, 0x28a0, v78
	s_waitcnt vmcnt(5)
; __device__ __forceinline__ unsigned cvt_pk_bf16(float lo, float hi) { unsigned r; asm volatile("v_cvt_pk_bf16_f32 %0, %1, %2" : "=v"(r) : "v"(lo), "v"(hi)); return r; }
; #define LAS __attribute__((address_space(3)))
; __device__ __forceinline__ void transpose_item(const float* W, int K, int N, bf16* WT, const float* gain, LAS float* scr, int item, int lane, bool ffn_perm) {
;     ...
;     for (int i = 0; i < 16; ++i) { LAS float* d = scr + (4 * i + lr) * 65 + lc; d[0] = v[i][0]; d[1] = v[i][1]; d[2] = v[i][2]; d[3] = v[i][3]; }
;     asm volatile("s_waitcnt lgkmcnt(0)" ::: "memory");
;     const int c = lane & 7;
;     f32x4 g0 = (f32x4){1.f, 1.f, 1.f, 1.f}, g1 = g0;
;     if (gain) { g0 = *(const f32x4*)(gain + k0 + 8 * c); g1 = *(const f32x4*)(gain + k0 + 8 * c + 4); }
; #pragma unroll
;     for (int j = 0; j < 8; ++j) { const int n = (lane >> 3) + 8 * j; const LAS float* s = scr + (8 * c) * 65 + n;
;         u32x4v o; o.x = cvt_pk_bf16(s[0 * 65] * g0[0], s[1 * 65] * g0[1]); o.y = cvt_pk_bf16(s[2 * 65] * g0[2], s[3 * 65] * g0[3]); o.z = cvt_pk_bf16(s[4 * 65] * g1[0], s[5 * 65] * g1[1]); o.w = cvt_pk_bf16(s[6 * 65] * g1[2], s[7 * 65] * g1[3]);
;         *(u32x4v*)(WT + (size_t)(d0 + n) * K + k0 + 8 * c) = o; }
;     asm volatile("s_waitcnt lgkmcnt(0)" ::: "memory");
	ds_write2_b32 v26, v22, v23 offset1:1
	v_add_u32_e32 v22, 0x28a8, v78
	ds_write2_b32 v22, v24, v25 offset1:1
	v_add_u32_e32 v22, 0x2cb0, v78
	s_waitcnt vmcnt(4)
	ds_write2_b32 v22, v18, v19 offset1:1
	v_add_u32_e32 v18, 0x2cb8, v78
	ds_write2_b32 v18, v20, v21 offset1:1
	v_add_u32_e32 v18, 0x30c0, v78
	s_waitcnt vmcnt(3)
	ds_write2_b32 v18, v14, v15 offset1:1
	v_add_u32_e32 v14, 0x30c8, v78
	ds_write2_b32 v14, v16, v17 offset1:1
	v_add_u32_e32 v14, 0x34d0, v78
	s_waitcnt vmcnt(2)
	ds_write2_b32 v14, v10, v11 offset1:1
	v_add_u32_e32 v10, 0x34d8, v78
	ds_write2_b32 v10, v12, v13 offset1:1
	v_add_u32_e32 v10, 0x38e0, v78
	s_waitcnt vmcnt(1)
	ds_write2_b32 v10, v6, v7 offset1:1
	v_add_u32_e32 v6, 0x38e8, v78
	ds_write2_b32 v6, v8, v9 offset1:1
	v_add_u32_e32 v6, 0x3cf0, v78
	v_add_u32_e32 v10, 0x400, v80
	s_waitcnt vmcnt(0)
	ds_write2_b32 v6, v2, v3 offset1:1
	v_add_u32_e32 v2, 0x3cf8, v78
	ds_write2_b32 v2, v4, v5 offset1:1
	s_waitcnt lgkmcnt(0)
	ds_read2_b32 v[2:3], v80 offset1:65
	s_waitcnt lgkmcnt(0)
	v_cvt_pk_bf16_f32 v2, v2, v3
	ds_read2_b32 v[4:5], v80 offset0:130 offset1:195
	s_waitcnt lgkmcnt(0)
	v_cvt_pk_bf16_f32 v3, v4, v5
	ds_read2_b32 v[4:5], v10 offset0:4 offset1:69
	s_waitcnt lgkmcnt(0)
	v_cvt_pk_bf16_f32 v4, v4, v5
	ds_read2_b32 v[8:9], v10 offset0:134 offset1:199
	s_waitcnt lgkmcnt(0)
	v_cvt_pk_bf16_f32 v5, v8, v9
	v_add_u32_e32 v8, s66, v83
	v_lshl_add_u64 v[6:7], s[10:11], 1, v[70:71]
	v_ashrrev_i32_e32 v9, 31, v8
	v_lshl_add_u64 v[12:13], v[8:9], 1, v[6:7]
	global_store_dwordx4 v102, v[2:5], s[100:101]
	ds_read2_b32 v[2:3], v80 offset0:8 offset1:73
	s_mul_i32 s10, s74, 0x58000
	s_waitcnt lgkmcnt(0)
	v_cvt_pk_bf16_f32 v2, v2, v3
	ds_read2_b32 v[4:5], v80 offset0:138 offset1:203
	s_waitcnt lgkmcnt(0)
	v_cvt_pk_bf16_f32 v3, v4, v5
	ds_read2_b32 v[4:5], v10 offset0:12 offset1:77
	s_waitcnt lgkmcnt(0)
	v_cvt_pk_bf16_f32 v4, v4, v5
	ds_read2_b32 v[12:13], v10 offset0:142 offset1:207
	s_waitcnt lgkmcnt(0)
	v_cvt_pk_bf16_f32 v5, v12, v13
	v_add_u32_e32 v12, 0xb000, v8
	v_ashrrev_i32_e32 v13, 31, v12
	v_lshl_add_u64 v[12:13], v[12:13], 1, v[6:7]
	global_store_dwordx4 v102, v[2:5], s[100:101] offset:256
	ds_read2_b32 v[2:3], v80 offset0:16 offset1:81
	v_add_u32_e32 v83, s10, v83
	s_waitcnt lgkmcnt(0)
	v_cvt_pk_bf16_f32 v2, v2, v3
	ds_read2_b32 v[4:5], v80 offset0:146 offset1:211
	s_waitcnt lgkmcnt(0)
	v_cvt_pk_bf16_f32 v3, v4, v5
	ds_read2_b32 v[4:5], v10 offset0:20 offset1:85
	s_waitcnt lgkmcnt(0)
	v_cvt_pk_bf16_f32 v4, v4, v5
	ds_read2_b32 v[12:13], v10 offset0:150 offset1:215
	s_waitcnt lgkmcnt(0)
	v_cvt_pk_bf16_f32 v5, v12, v13
	v_add_u32_e32 v12, 0x16000, v8
	v_ashrrev_i32_e32 v13, 31, v12
	v_lshl_add_u64 v[12:13], v[12:13], 1, v[6:7]
	global_store_dwordx4 v103, v[2:5], s[100:101] offset:512
	ds_read2_b32 v[2:3], v80 offset0:24 offset1:89
	s_waitcnt lgkmcnt(0)
	v_cvt_pk_bf16_f32 v2, v2, v3
	ds_read2_b32 v[4:5], v80 offset0:154 offset1:219
	s_waitcnt lgkmcnt(0)
	v_cvt_pk_bf16_f32 v3, v4, v5
	ds_read2_b32 v[4:5], v10 offset0:28 offset1:93
	s_waitcnt lgkmcnt(0)
	v_cvt_pk_bf16_f32 v4, v4, v5
	ds_read2_b32 v[12:13], v10 offset0:158 offset1:223
	s_waitcnt lgkmcnt(0)
	v_cvt_pk_bf16_f32 v5, v12, v13
	v_add_u32_e32 v12, 0x21000, v8
	v_ashrrev_i32_e32 v13, 31, v12
	v_lshl_add_u64 v[12:13], v[12:13], 1, v[6:7]
	global_store_dwordx4 v103, v[2:5], s[100:101] offset:768
	ds_read2_b32 v[2:3], v80 offset0:32 offset1:97
	s_waitcnt lgkmcnt(0)
	v_cvt_pk_bf16_f32 v2, v2, v3
	ds_read2_b32 v[4:5], v80 offset0:162 offset1:227
	s_waitcnt lgkmcnt(0)
	v_cvt_pk_bf16_f32 v3, v4, v5
	ds_read2_b32 v[4:5], v10 offset0:36 offset1:101
	s_waitcnt lgkmcnt(0)
	v_cvt_pk_bf16_f32 v4, v4, v5
	ds_read2_b32 v[12:13], v10 offset0:166 offset1:231
	s_waitcnt lgkmcnt(0)
	v_cvt_pk_bf16_f32 v5, v12, v13
	v_add_u32_e32 v12, 0x2c000, v8
	v_ashrrev_i32_e32 v13, 31, v12
	v_lshl_add_u64 v[12:13], v[12:13], 1, v[6:7]
	global_store_dwordx4 v100, v[2:5], s[100:101]
	ds_read2_b32 v[2:3], v80 offset0:40 offset1:105
	s_waitcnt lgkmcnt(0)
	v_cvt_pk_bf16_f32 v2, v2, v3
	ds_read2_b32 v[4:5], v80 offset0:170 offset1:235
	s_waitcnt lgkmcnt(0)
	v_cvt_pk_bf16_f32 v3, v4, v5
	ds_read2_b32 v[4:5], v10 offset0:44 offset1:109
	s_waitcnt lgkmcnt(0)
	v_cvt_pk_bf16_f32 v4, v4, v5
	ds_read2_b32 v[12:13], v10 offset0:174 offset1:239
	s_waitcnt lgkmcnt(0)
	v_cvt_pk_bf16_f32 v5, v12, v13
	v_add_u32_e32 v12, 0x37000, v8
	v_ashrrev_i32_e32 v13, 31, v12
	v_lshl_add_u64 v[12:13], v[12:13], 1, v[6:7]
	global_store_dwordx4 v100, v[2:5], s[100:101] offset:256
	ds_read2_b32 v[2:3], v80 offset0:48 offset1:113
	s_waitcnt lgkmcnt(0)
	v_cvt_pk_bf16_f32 v2, v2, v3
	ds_read2_b32 v[4:5], v80 offset0:178 offset1:243
	s_waitcnt lgkmcnt(0)
	v_cvt_pk_bf16_f32 v3, v4, v5
	ds_read2_b32 v[4:5], v10 offset0:52 offset1:117
	s_waitcnt lgkmcnt(0)
	v_cvt_pk_bf16_f32 v4, v4, v5
	ds_read2_b32 v[12:13], v10 offset0:182 offset1:247
	s_waitcnt lgkmcnt(0)
	v_cvt_pk_bf16_f32 v5, v12, v13
	v_add_u32_e32 v12, 0x42000, v8
	v_ashrrev_i32_e32 v13, 31, v12
	v_lshl_add_u64 v[12:13], v[12:13], 1, v[6:7]
	global_store_dwordx4 v101, v[2:5], s[100:101] offset:512
	ds_read2_b32 v[2:3], v80 offset0:56 offset1:121
	v_add_u32_e32 v8, 0x4d000, v8
	s_waitcnt lgkmcnt(0)
	v_cvt_pk_bf16_f32 v2, v2, v3
	ds_read2_b32 v[4:5], v80 offset0:186 offset1:251
	v_ashrrev_i32_e32 v9, 31, v8
	s_waitcnt lgkmcnt(0)
	v_cvt_pk_bf16_f32 v3, v4, v5
	ds_read2_b32 v[4:5], v10 offset0:60 offset1:125
	v_lshl_add_u64 v[6:7], v[8:9], 1, v[6:7]
	s_waitcnt lgkmcnt(0)
	v_cvt_pk_bf16_f32 v4, v4, v5
	ds_read2_b32 v[10:11], v10 offset0:190 offset1:255
	s_waitcnt lgkmcnt(0)
	v_cvt_pk_bf16_f32 v5, v10, v11
	global_store_dwordx4 v101, v[2:5], s[100:101] offset:768
	s_waitcnt lgkmcnt(0)
	s_cbranch_scc1 .LBB0_473
	s_branch .LBB0_463
